# FF2 stream-K locality: first-region (38 K-tile) workgroup pairs 32 apart also share a row panel
# speedup vs baseline: 1.0262x; 1.0015x over previous
.LBB0_411:
	s_or_b64 exec, exec, s[0:1]
	s_cmpk_lt_i32 s2, 0x330
	s_mul_hi_i32 s0, s2, 0xa0a0a0a1
	s_cselect_b64 s[26:27], -1, 0
	s_add_i32 s0, s0, s2
	s_lshr_b32 s1, s0, 31
	s_lshr_b32 s0, s0, 9
	s_add_i32 s0, s0, s1
	s_mulk_i32 s0, 0x330
	s_sub_i32 s0, s2, s0
	s_sext_i32_i16 s1, s0
	s_bfe_u32 s1, s1, 0x3001c
	s_add_i32 s1, s0, s1
	s_sext_i32_i16 s3, s1
	s_and_b32 s1, s1, 0xfff8
	s_ashr_i32 s6, s3, 3
	s_sub_i32 s8, s0, s1
	s_sub_i32 s80, s94, 48
	s_sub_i32 s0, s2, 48
	s_cmp_gt_u32 s2, 47
	s_cselect_b32 s81, s0, 0x10000000
	s_cmpk_lt_i32 s81, 0x198
	s_cselect_b64 s[0:1], -1, 0
	v_writelane_b32 v245, s0, 3
	s_waitcnt lgkmcnt(0)
	v_mov_b32_e32 v0, 0xe0
	v_sub_co_u32_e32 v0, vcc, s2, v0
	v_writelane_b32 v245, s1, 4
	s_mul_hi_i32 s0, s81, 0xa0a0a0a1
	s_add_i32 s0, s0, s81
	s_lshr_b32 s1, s0, 31
	s_lshr_b32 s0, s0, 8
	s_add_i32 s0, s0, s1
	s_mulk_i32 s0, 0x198
	s_sub_i32 s0, s81, s0
	s_sext_i32_i16 s1, s0
	s_bfe_u32 s1, s1, 0x3001c
	s_add_i32 s1, s0, s1
	s_sext_i32_i16 s3, s1
	s_and_b32 s1, s1, 0xfff8
	s_ashr_i32 s5, s3, 3
	s_sub_i32 s7, s0, s1
	s_cmpk_lt_i32 s2, 0x110
	s_cselect_b64 s[0:1], -1, 0
	v_writelane_b32 v245, s0, 5
	s_bfe_u32 s87, s2, 0x50002
	s_lshr_b32 s3, s2, 2
	v_writelane_b32 v245, s1, 6
	s_and_b32 s0, s2, 3
	s_lshl_b32 s89, s87, 6
	s_lshl_b32 s1, s0, 2
	s_lshl_b32 s0, s0, 8
	s_cmp_lg_u32 s87, 0
	v_writelane_b32 v245, s1, 7
	s_cselect_b64 s[36:37], -1, 0
	s_cmp_eq_u32 s87, 31
	v_writelane_b32 v245, s0, 8
	s_cselect_b64 s[38:39], -1, 0
	s_lshl_b32 s0, s2, 8
	s_and_b32 s0, s0, 0x300
	s_cmp_eq_u32 s87, 0
	v_writelane_b32 v245, s0, 9
	s_cselect_b64 s[0:1], -1, 0
	v_writelane_b32 v245, s0, 10
	s_cmp_gt_u32 s87, 1
	s_movk_i32 s93, 0x67
	v_writelane_b32 v245, s1, 11
	s_cselect_b64 s[0:1], -1, 0
	v_writelane_b32 v245, s0, 12
	s_cmp_gt_u32 s87, 2
	v_mov_b32_e32 v185, 0
	v_writelane_b32 v245, s1, 13
	s_cselect_b64 s[0:1], -1, 0
	v_writelane_b32 v245, s0, 14
	s_cmp_gt_u32 s87, 3
	v_mov_b32_e32 v216, 0x358637bd
	v_writelane_b32 v245, s1, 15
	s_cselect_b64 s[0:1], -1, 0
	v_writelane_b32 v245, s0, 16
	s_cmp_gt_u32 s87, 4
	v_mov_b32_e32 v217, 0x1000
	v_writelane_b32 v245, s1, 17
	s_cselect_b64 s[0:1], -1, 0
	v_writelane_b32 v245, s0, 18
	s_cmp_gt_u32 s87, 5
	v_mov_b32_e32 v218, 0x2000
	v_writelane_b32 v245, s1, 19
	s_cselect_b64 s[0:1], -1, 0
	v_writelane_b32 v245, s0, 20
	s_cmp_gt_u32 s87, 6
	v_mov_b32_e32 v219, 0x11083000
	v_writelane_b32 v245, s1, 21
	s_cselect_b64 s[0:1], -1, 0
	v_writelane_b32 v245, s0, 22
	s_cmp_gt_u32 s87, 7
	v_mov_b32_e32 v220, 1
	v_writelane_b32 v245, s1, 23
	s_cselect_b64 s[0:1], -1, 0
	v_writelane_b32 v245, s0, 24
	s_cmp_gt_u32 s87, 8
	v_mov_b32_e32 v222, 0x3000
	v_writelane_b32 v245, s1, 25
	s_cselect_b64 s[0:1], -1, 0
	s_cmp_gt_u32 s87, 9
	s_cselect_b64 s[40:41], -1, 0
	s_cmp_gt_u32 s87, 10
	s_cselect_b64 s[42:43], -1, 0
	s_cmp_gt_u32 s87, 11
	s_cselect_b64 s[44:45], -1, 0
	s_cmp_gt_u32 s87, 12
	s_cselect_b64 s[46:47], -1, 0
	s_cmp_gt_u32 s87, 13
	v_writelane_b32 v245, s0, 26
	s_cselect_b64 s[48:49], -1, 0
	s_cmp_gt_u32 s87, 14
	v_writelane_b32 v245, s1, 27
	s_cselect_b64 s[0:1], -1, 0
	v_writelane_b32 v245, s0, 28
	s_cmp_gt_u32 s87, 15
	v_mov_b32_e32 v223, 0x2200
	v_writelane_b32 v245, s1, 29
	s_cselect_b64 s[0:1], -1, 0
	v_writelane_b32 v245, s0, 30
	s_cmp_gt_u32 s87, 16
	s_movk_i32 s90, 0x4000
	v_writelane_b32 v245, s1, 31
	s_cselect_b64 s[0:1], -1, 0
	v_writelane_b32 v245, s0, 32
	s_cmp_gt_u32 s87, 17
	s_movk_i32 s68, 0x4800
	v_writelane_b32 v245, s1, 33
	s_cselect_b64 s[0:1], -1, 0
	v_writelane_b32 v245, s0, 34
	s_cmp_gt_u32 s87, 18
	s_mov_b32 s69, 0xffff0000
	v_writelane_b32 v245, s1, 35
	s_cselect_b64 s[0:1], -1, 0
	v_writelane_b32 v245, s0, 36
	s_cmp_gt_u32 s87, 19
	s_movk_i32 s50, 0x3000
	v_writelane_b32 v245, s1, 37
	s_cselect_b64 s[0:1], -1, 0
	v_writelane_b32 v245, s0, 38
	s_cmp_gt_u32 s87, 20
	s_mov_b32 s52, 0
	v_writelane_b32 v245, s1, 39
	s_cselect_b64 s[0:1], -1, 0
	v_writelane_b32 v245, s0, 40
	s_cmp_gt_u32 s87, 21
	s_mov_b32 s97, 0
	v_writelane_b32 v245, s1, 41
	s_cselect_b64 s[0:1], -1, 0
	v_writelane_b32 v245, s0, 42
	s_cmp_gt_u32 s87, 22
	s_nop 0
	v_writelane_b32 v245, s1, 43
	s_cselect_b64 s[0:1], -1, 0
	v_writelane_b32 v245, s0, 44
	s_cmp_gt_u32 s87, 23
	s_barrier
	v_writelane_b32 v245, s1, 45
	s_cselect_b64 s[0:1], -1, 0
	v_writelane_b32 v245, s0, 46
	s_cmp_gt_u32 s87, 24
	s_nop 0
	v_writelane_b32 v245, s1, 47
	s_cselect_b64 s[0:1], -1, 0
	v_writelane_b32 v245, s0, 48
	s_cmp_gt_u32 s87, 25
	s_nop 0
	v_writelane_b32 v245, s1, 49
	s_cselect_b64 s[0:1], -1, 0
	v_writelane_b32 v245, s0, 50
	s_cmp_gt_u32 s87, 26
	s_nop 0
	v_writelane_b32 v245, s1, 51
	s_cselect_b64 s[0:1], -1, 0
	v_writelane_b32 v245, s0, 52
	s_cmp_gt_u32 s87, 27
	s_nop 0
	v_writelane_b32 v245, s1, 53
	s_cselect_b64 s[0:1], -1, 0
	v_writelane_b32 v245, s0, 54
	s_cmp_gt_u32 s87, 28
	s_nop 0
	v_writelane_b32 v245, s1, 55
	s_cselect_b64 s[0:1], -1, 0
	v_writelane_b32 v245, s0, 56
	s_cmp_gt_u32 s87, 29
	s_nop 0
	v_writelane_b32 v245, s1, 57
	s_cselect_b64 s[0:1], -1, 0
	v_writelane_b32 v245, s0, 58
	s_nop 1
	v_writelane_b32 v245, s1, 59
	v_sub_co_u32_e64 v214, s[0:1], s2, 32
	s_xor_b64 s[0:1], s[0:1], -1
	s_nop 0
	v_writelane_b32 v245, s0, 60
	s_nop 1
	v_writelane_b32 v245, s1, 61
	s_sub_i32 s0, s94, 32
	v_writelane_b32 v245, s0, 62
	s_lshl_b32 s0, s3, 6
	s_addk_i32 s0, 0x2000
	v_writelane_b32 v245, s0, 63
	s_lshl_b32 s0, s3, 3
	s_cmpk_lt_i32 s2, 0x198
	v_writelane_b32 v244, s0, 0
	s_mul_hi_i32 s0, s2, 0x78787879
	s_cselect_b64 s[10:11], -1, 0
	v_writelane_b32 v244, s10, 1
	s_lshr_b32 s1, s0, 31
	s_ashr_i32 s0, s0, 6
	v_writelane_b32 v244, s11, 2
	s_add_i32 s10, s0, s1
	s_mul_i32 s0, s10, 0x88
	s_sub_i32 s0, s2, s0
	s_bfe_u32 s1, s0, 0x3001c
	s_add_i32 s1, s0, s1
	s_and_b32 s3, s1, 0xfff8
	s_sub_i32 s9, s0, s3
	s_sext_i32_i16 s0, s1
	s_ashr_i32 s11, s10, 31
	s_ashr_i32 s14, s0, 3
	s_lshl_b64 s[0:1], s[10:11], 11
	v_writelane_b32 v244, s0, 3
	s_nop 1
	v_writelane_b32 v244, s1, 4
	s_mov_b32 s0, s10
	v_writelane_b32 v244, s0, 5
	s_nop 1
	v_writelane_b32 v244, s1, 6
	s_lshl_b64 s[0:1], s[10:11], 21
	v_writelane_b32 v244, s0, 7
	s_cmpk_lt_i32 s2, 0x88
	s_nop 0
	v_writelane_b32 v244, s1, 8
	s_cselect_b64 s[0:1], -1, 0
	v_writelane_b32 v244, s0, 9
	s_cmpk_gt_u32 s2, 0x87
	s_nop 0
	v_writelane_b32 v244, s1, 10
	s_cselect_b64 s[0:1], -1, 0
	v_writelane_b32 v244, s0, 11
	s_nop 1
	v_writelane_b32 v244, s1, 12
	s_add_i32 s0, s84, 0xfffffbc0
	v_writelane_b32 v244, s0, 13
	s_add_i32 s0, s88, 0xfffffbc0
	s_cmpk_lt_i32 s2, 0x200
	v_writelane_b32 v244, s0, 14
	s_cselect_b64 s[0:1], -1, 0
	v_writelane_b32 v244, s0, 15
	s_ashr_i32 s3, s2, 31
	s_and_b32 s12, s2, 15
	v_writelane_b32 v244, s1, 16
	s_lshr_b32 s0, s3, 23
	s_add_i32 s0, s2, s0
	s_and_b32 s0, s0, 0xfe00
	s_sub_i32 s0, s2, s0
	s_sext_i32_i16 s1, s0
	s_bfe_u32 s1, s1, 0x3001c
	s_add_i32 s1, s0, s1
	s_and_b32 s4, s1, 0xfff8
	s_sub_i32 s15, s0, s4
	s_sext_i32_i16 s0, s1
	s_ashr_i32 s16, s0, 3
	v_readfirstlane_b32 s0, v0
	s_ashr_i32 s4, s0, 4
	s_add_i32 s10, s4, 32
	s_lshl_b32 s0, s4, 5
	s_ashr_i32 s11, s10, 31
	s_lshl_b32 s13, s12, 19
	s_ashr_i32 s1, s0, 31
	s_lshl_b32 s17, s15, 6
	v_writelane_b32 v244, s13, 17
	s_lshl_b64 s[18:19], s[10:11], 19
	v_writelane_b32 v244, s18, 18
	s_cmp_gt_i32 s4, -1
	s_nop 0
	v_writelane_b32 v244, s19, 19
	s_cselect_b64 s[18:19], -1, 0
	v_writelane_b32 v244, s18, 20
	s_ashr_i32 s11, s10, 3
	s_lshl_b32 s13, s10, 8
	v_writelane_b32 v244, s19, 21
	v_writelane_b32 v244, s11, 22
	s_lshl_b32 s10, s12, 8
	v_writelane_b32 v244, s10, 23
	s_and_b32 s56, s2, 7
	s_lshr_b32 s57, s2, 3
	s_sub_i32 s57, s57, 8
	s_lshr_b32 s58, s57, 1
	s_lshl_b32 s58, s58, 4
	s_lshl_b32 s56, s56, 1
	s_add_i32 s58, s58, s56
	s_and_b32 s57, s57, 1
	s_add_i32 s58, s58, s57
	s_add_i32 s58, s58, 64
	s_sub_i32 s57, s2, 64
	s_cmpk_lt_u32 s57, 0xa0
	s_cselect_b32 s54, s58, s2
	s_mov_b32 s55, 0
	s_lshl_b32 s10, s54, 4
	s_add_i32 s11, s10, 0x1200
	s_mul_i32 s10, s54, 36
	s_add_i32 s18, s10, 0x80
	s_or_b32 s10, s13, 0x80
	v_writelane_b32 v244, s10, 24
	s_or_b32 s10, s13, 0x90
	v_writelane_b32 v244, s10, 25
	s_or_b32 s10, s13, 0xa0
	v_writelane_b32 v244, s10, 26
	v_writelane_b32 v244, s13, 27
	s_or_b32 s10, s13, 0xb0
	v_writelane_b32 v244, s10, 28
	s_add_i32 s10, s54, 1
	s_cmpk_lt_u32 s10, 0xe0
	s_cselect_b32 s12, 36, 16
	s_cmp_gt_i32 s54, 62
	s_cselect_b32 s19, s12, 38
	s_add_i32 s12, s54, 2
	s_cmpk_lt_u32 s12, 0xe0
	s_cselect_b32 s12, 36, 16
	s_cmp_gt_i32 s54, 61
	s_cselect_b32 s12, s12, 38
	s_add_i32 s20, s19, s12
	s_cmpk_gt_u32 s2, 0xdf
	s_cselect_b64 s[12:13], -1, 0
	v_writelane_b32 v244, s12, 29
	s_nop 1
	v_writelane_b32 v244, s13, 30
	s_and_b64 s[12:13], s[12:13], exec
	s_cselect_b32 s21, 16, 36
	s_cselect_b32 s22, s11, s18
	s_and_b64 s[12:13], vcc, exec
	s_cselect_b32 s11, s18, s11
	s_cmp_lt_i32 s54, 64
	s_mul_i32 s12, s54, 38
	s_cselect_b32 s13, s12, s22
	s_cselect_b32 s18, s12, s11
	s_cselect_b32 s21, 38, s21
	s_and_b32 s12, s13, 62
	s_ashr_i32 s11, s13, 6
	s_sub_i32 s12, 64, s12
	s_cmp_lt_u32 s12, s21
	v_mov_b32_e32 v0, s12
	s_cselect_b64 s[12:13], -1, 0
	v_sub_u32_e64 v0, s21, v0 clamp
	v_writelane_b32 v244, s12, 31
	s_add_i32 s11, s11, 1
	v_writelane_b32 v244, s13, 32
	s_lshr_b32 s92, s11, 2
	s_and_b32 s28, s11, 3
	s_sub_i32 s60, s11, 38
	s_mul_i32 s61, s60, 57
	s_lshr_b32 s61, s61, 9
	s_mul_i32 s62, s61, 9
	s_sub_i32 s62, s60, s62
	s_mul_i32 s62, s62, 3
	s_lshr_b32 s63, s61, 2
	s_add_i32 s62, s62, s63
	s_and_b32 s63, s61, 3
	s_cmpk_lt_u32 s11, 0x80
	s_cselect_b32 s92, s62, s92
	s_cselect_b32 s28, s63, s28
	s_sub_i32 s60, s11, 19
	s_cmpk_lt_u32 s11, 19
	s_cselect_b32 s60, s11, s60
	s_cselect_b32 s61, 0, 1
	s_mul_i32 s62, s60, 3
	s_add_i32 s62, s62, 2
	s_add_i32 s63, s61, 2
	s_sub_i32 s64, s60, 9
	s_lshr_b32 s65, s64, 1
	s_add_i32 s65, s65, 27
	s_and_b32 s64, s64, 1
	s_lshl_b32 s64, s64, 1
	s_add_i32 s64, s64, s61
	s_cmpk_lt_u32 s60, 9
	s_cselect_b32 s62, s62, s65
	s_cselect_b32 s63, s63, s64
	s_cmpk_lt_u32 s11, 38
	s_cselect_b32 s92, s62, s92
	s_cselect_b32 s28, s63, s28
	v_readfirstlane_b32 s11, v0
	s_nop 1
	v_writelane_b32 v244, s11, 33
	s_sub_i32 s11, 64, s11
	s_cmp_gt_u32 s11, s19
	s_cselect_b32 s22, 2, 1
	s_cmp_gt_u32 s11, s20
	s_cselect_b64 s[12:13], -1, 0
	s_cmp_lg_u64 s[12:13], 0
	s_addc_u32 s11, s22, 0
	v_writelane_b32 v244, s11, 34
	s_ashr_i32 s11, s10, 31
	s_lshl_b64 s[10:11], s[10:11], 17
	v_writelane_b32 v244, s10, 35
	s_lshl_b64 s[12:13], s[54:55], 17
	s_nop 0
	v_writelane_b32 v244, s11, 36
	s_sext_i32_i16 s10, s8
	s_cmp_lt_i32 s10, 0
	s_cselect_b32 s10, s93, 0x66
	s_mul_i32 s8, s10, s8
	s_add_i32 s8, s8, s6
	s_sext_i32_i16 s6, s8
	s_mulk_i32 s6, 0x2aab
	s_lshr_b32 s10, s6, 31
	s_ashr_i32 s6, s6, 21
	s_add_i32 s6, s6, s10
	s_mul_i32 s10, s6, 0xc0
	s_sext_i32_i16 s6, s6
	s_lshl_b32 s11, s6, 3
	v_writelane_b32 v244, s12, 37
	s_sub_i32 s6, 34, s11
	s_sub_i32 s10, s8, s10
	v_writelane_b32 v244, s13, 38
	s_min_u32 s12, s6, 8
	s_sext_i32_i16 s6, s7
	s_cmp_lt_i32 s6, 0
	s_cselect_b32 s6, 52, 51
	s_mul_i32 s6, s6, s7
	s_add_i32 s6, s6, s5
	s_sext_i32_i16 s5, s6
	s_mulk_i32 s5, 0x2aab
	s_lshr_b32 s7, s5, 31
	s_ashr_i32 s5, s5, 20
	s_add_i32 s5, s5, s7
	s_mul_i32 s7, s5, 0x60
	s_sext_i32_i16 s5, s5
	s_lshl_b32 s5, s5, 3
	s_sub_i32 s13, s6, s7
	s_sub_i32 s6, 34, s5
	s_min_u32 s22, s6, 8
	s_sext_i32_i16 s6, s9
	s_cmp_lt_i32 s6, 0
	s_cselect_b32 s6, 18, 17
	s_mul_i32 s6, s6, s9
	s_add_i32 s6, s6, s14
	s_sext_i32_i16 s7, s6
	s_bfe_u32 s7, s7, 0x5001a
	s_add_i32 s7, s6, s7
	s_and_b32 s8, s7, 0xffe0
	s_sub_i32 s14, s6, s8
	s_sext_i32_i16 s6, s7
	s_ashr_i32 s6, s6, 5
	s_lshl_b32 s23, s6, 3
	s_sub_i32 s6, 34, s23
	s_min_u32 s24, s6, 8
	s_sext_i32_i16 s6, s15
	s_cmp_lt_i32 s6, 0
	s_mulk_i32 s15, 0x41
	s_cselect_b32 s6, s15, s17
	s_add_i32 s6, s6, s16
	s_sext_i32_i16 s7, s6
	s_bfe_u32 s7, s7, 0x70018
	s_add_i32 s7, s6, s7
	s_and_b32 s8, s7, 0xff80
	s_sub_i32 s6, s6, s8
	s_bfe_i32 s8, s6, 0x80000
	s_bfe_u32 s8, s8, 0x3000c
	s_add_i32 s8, s6, s8
	s_and_b32 s9, s8, 0xf8
	s_sext_i32_i16 s7, s7
	s_sub_i32 s6, s6, s9
	s_and_b32 s15, s18, 62
	s_ashr_i32 s7, s7, 7
	s_bfe_i32 s8, s8, 0x80000
	s_sub_i32 s9, 64, s15
	s_lshl_b32 s7, s7, 3
	s_sext_i32_i16 s8, s8
	s_sext_i32_i8 s6, s6
	s_min_u32 s9, s9, s21
	s_add_i32 s30, s7, s6
	s_ashr_i32 s6, s8, 3
	v_writelane_b32 v244, s6, 39
	s_lshr_b32 s6, s8, 3
	s_lshr_b32 s56, s18, 6
	s_lshr_b32 s18, s56, 2
	s_and_b32 s17, s56, 3
	s_sub_i32 s60, s56, 38
	s_mul_i32 s61, s60, 57
	s_lshr_b32 s61, s61, 9
	s_mul_i32 s62, s61, 9
	s_sub_i32 s62, s60, s62
	s_mul_i32 s62, s62, 3
	s_lshr_b32 s63, s61, 2
	s_add_i32 s62, s62, s63
	s_and_b32 s63, s61, 3
	s_cmpk_lt_u32 s56, 0x80
	s_cselect_b32 s18, s62, s18
	s_cselect_b32 s17, s63, s17
	s_sub_i32 s60, s56, 19
	s_cmpk_lt_u32 s56, 19
	s_cselect_b32 s60, s56, s60
	s_cselect_b32 s61, 0, 1
	s_mul_i32 s62, s60, 3
	s_add_i32 s62, s62, 2
	s_add_i32 s63, s61, 2
	s_sub_i32 s64, s60, 9
	s_lshr_b32 s65, s64, 1
	s_add_i32 s65, s65, 27
	s_and_b32 s64, s64, 1
	s_lshl_b32 s64, s64, 1
	s_add_i32 s64, s64, s61
	s_cmpk_lt_u32 s60, 9
	s_cselect_b32 s62, s62, s65
	s_cselect_b32 s63, s63, s64
	s_cmpk_lt_u32 s56, 38
	s_cselect_b32 s18, s62, s18
	s_cselect_b32 s17, s63, s17
	s_sub_i32 s7, 64, s9
	s_cmp_gt_u32 s7, s19
	s_cselect_b32 s16, 2, 1
	s_cmp_gt_u32 s7, s20
	v_writelane_b32 v244, s9, 40
	s_cselect_b64 s[8:9], -1, 0
	s_cmp_lg_u64 s[8:9], 0
	s_addc_u32 s8, s16, 0
	s_bfe_i64 s[6:7], s[6:7], 0x100000
	s_lshl_b64 s[6:7], s[6:7], 19
	v_writelane_b32 v244, s6, 41
	s_ashr_i32 s19, s18, 31
	s_ashr_i32 s31, s30, 31
	v_writelane_b32 v244, s7, 42
	s_lshl_b32 s6, s15, 7
	v_writelane_b32 v244, s6, 43
	v_writelane_b32 v244, s17, 44
	s_lshl_b32 s6, s17, 21
	v_writelane_b32 v244, s6, 45
	s_mov_b32 s6, s18
	v_writelane_b32 v244, s6, 46
	v_cvt_f32_ubyte0_e32 v1, s12
	v_rcp_iflag_f32_e32 v2, v1
	v_writelane_b32 v244, s7, 47
	s_lshl_b64 s[6:7], s[18:19], 21
	v_writelane_b32 v244, s6, 48
	s_nop 1
	v_writelane_b32 v244, s7, 49
	s_mov_b32 s6, s30
	v_writelane_b32 v244, s6, 50
	s_nop 1
	v_writelane_b32 v244, s7, 51
	s_lshl_b64 s[6:7], s[30:31], 19
	v_writelane_b32 v244, s6, 52
	s_cmp_eq_u32 s15, 0
	s_nop 0
	v_writelane_b32 v244, s7, 53
	s_cselect_b32 s6, s8, 0
	v_writelane_b32 v244, s6, 54
	s_sext_i32_i16 s6, s10
	v_cvt_f32_i32_e32 v0, s6
	s_cselect_b32 s7, 2, 1
	s_ashr_i32 s6, s6, 30
	v_writelane_b32 v244, s7, 55
	v_mul_f32_e32 v2, v0, v2
	v_trunc_f32_e32 v2, v2
	v_fma_f32 v0, -v2, v1, v0
	s_or_b32 s8, s6, 1
	v_cmp_ge_f32_e64 s[6:7], |v0|, v1
	v_cvt_i32_f32_e32 v0, v2
	s_and_b64 s[6:7], s[6:7], exec
	s_cselect_b32 s6, s8, 0
	v_cvt_f32_ubyte0_e32 v1, s22
	v_readfirstlane_b32 s7, v0
	s_add_i32 s15, s7, s6
	s_mul_i32 s6, s15, s12
	s_sub_i32 s6, s10, s6
	s_sext_i32_i16 s6, s6
	s_add_i32 s6, s11, s6
	v_writelane_b32 v244, s6, 56
	s_sext_i32_i16 s6, s13
	v_cvt_f32_i32_e32 v0, s6
	v_rcp_iflag_f32_e32 v2, v1
	s_ashr_i32 s6, s6, 30
	s_or_b32 s8, s6, 1
	v_mul_f32_e32 v2, v0, v2
	v_trunc_f32_e32 v2, v2
	v_fma_f32 v0, -v2, v1, v0
	v_cmp_ge_f32_e64 s[6:7], |v0|, v1
	v_cvt_i32_f32_e32 v0, v2
	s_and_b64 s[6:7], s[6:7], exec
	s_cselect_b32 s6, s8, 0
	v_cvt_f32_ubyte0_e32 v1, s24
	v_readfirstlane_b32 s7, v0
	s_add_i32 s6, s7, s6
	s_mul_i32 s7, s6, s22
	s_sub_i32 s7, s13, s7
	s_sext_i32_i8 s7, s7
	s_add_i32 s10, s5, s7
	s_sext_i32_i16 s5, s14
	v_cvt_f32_i32_e32 v0, s5
	v_rcp_iflag_f32_e32 v2, v1
	s_bfe_i64 s[8:9], s[6:7], 0x80000
	s_lshl_b64 s[8:9], s[8:9], 18
	v_writelane_b32 v244, s8, 57
	s_ashr_i32 s11, s10, 31
	v_mul_f32_e32 v2, v0, v2
	v_writelane_b32 v244, s9, 58
	s_mov_b32 s8, s10
	v_writelane_b32 v244, s8, 59
	v_trunc_f32_e32 v2, v2
	v_fma_f32 v0, -v2, v1, v0
	v_writelane_b32 v244, s9, 60
	s_lshl_b64 s[8:9], s[10:11], 18
	v_writelane_b32 v244, s8, 61
	s_ashr_i32 s5, s5, 30
	s_or_b32 s5, s5, 1
	v_writelane_b32 v244, s9, 62
	v_cmp_ge_f32_e64 s[8:9], |v0|, v1
	v_cvt_i32_f32_e32 v0, v2
	s_and_b64 s[8:9], s[8:9], exec
	v_writelane_b32 v244, s26, 63
	s_sext_i32_i8 s6, s6
	s_cselect_b32 s5, s5, 0
	v_writelane_b32 v243, s27, 0
	v_writelane_b32 v243, s6, 1
	v_readfirstlane_b32 s6, v0
	s_add_i32 s6, s6, s5
	s_mul_i32 s5, s6, s24
	s_sub_i32 s5, s14, s5
	s_sext_i32_i8 s5, s5
	s_add_i32 s5, s23, s5
	s_mul_i32 s7, s95, s94
	v_writelane_b32 v243, s5, 2
	s_sext_i32_i16 s5, s15
	s_mul_i32 s95, s7, s33
	v_writelane_b32 v243, s5, 3
	s_sext_i32_i8 s5, s6
	s_bfe_i64 s[6:7], s[6:7], 0x80000
	v_writelane_b32 v243, s5, 4
	s_lshl_b64 s[6:7], s[6:7], 19
	v_writelane_b32 v243, s6, 5
	s_ashr_i32 s5, s4, 31
	s_lshl_b64 s[4:5], s[4:5], 19
	v_writelane_b32 v243, s7, 6
	v_writelane_b32 v243, s4, 7
	s_lshl_b64 s[0:1], s[0:1], 2
	s_ashr_i32 s85, s84, 31
	v_writelane_b32 v243, s5, 8
	v_writelane_b32 v243, s0, 9
	s_lshl_b32 s4, s94, 5
	v_mbcnt_lo_u32_b32 v0, -1, 0
	v_writelane_b32 v243, s1, 10
	v_writelane_b32 v243, s84, 11
	s_add_i32 s1, s84, 0xfffff800
	s_movk_i32 s0, 0x110
	v_writelane_b32 v243, s85, 12
	v_writelane_b32 v243, s1, 13
	s_lshl_b32 s1, s2, 5
	v_writelane_b32 v243, s1, 14
	s_addk_i32 s1, 0xdc00
	v_writelane_b32 v243, s1, 15
	v_writelane_b32 v243, s4, 16
	s_add_i32 s1, s4, 0xfffffc00
	v_writelane_b32 v243, s1, 17
	s_lshl_b32 s1, s94, 10
	v_writelane_b32 v243, s1, 18
	s_lshl_b32 s1, s2, 12
	v_writelane_b32 v243, s1, 19
	s_lshl_b32 s1, s94, 14
	v_writelane_b32 v243, s1, 20
	s_add_i32 s1, 0, 0x20000
	v_writelane_b32 v243, s1, 21
	s_add_i32 s1, 0, 0x20004
	v_writelane_b32 v243, s1, 22
	v_cmp_gt_i32_e64 s[0:1], s0, v214
	v_cndmask_b32_e64 v215, 0, 1, s[26:27]
	v_mbcnt_hi_u32_b32 v221, -1, v0
	v_writelane_b32 v243, s0, 23
	s_movk_i32 s33, 0x2000
	s_mov_b32 s84, s28
	v_writelane_b32 v243, s1, 24
	v_cmp_gt_u32_e64 s[0:1], 64, v195
	s_mov_b64 s[4:5], 0x80
	s_nop 0
	v_writelane_b32 v243, s0, 25
	s_nop 1
	v_writelane_b32 v243, s1, 26
	s_lshl_b64 s[0:1], s[54:55], 2
	v_writelane_b32 v243, s0, 27
	s_nop 1
	v_writelane_b32 v243, s1, 28
	v_writelane_b32 v243, s36, 29
	s_nop 1
	v_writelane_b32 v243, s37, 30
	v_writelane_b32 v243, s38, 31
	s_nop 1
	v_writelane_b32 v243, s39, 32
	v_writelane_b32 v243, s40, 33
	s_nop 1
	v_writelane_b32 v243, s41, 34
	v_writelane_b32 v243, s42, 35
	s_nop 1
	v_writelane_b32 v243, s43, 36
	v_writelane_b32 v243, s44, 37
	s_nop 1
	v_writelane_b32 v243, s45, 38
	v_writelane_b32 v243, s46, 39
	s_nop 1
	v_writelane_b32 v243, s47, 40
	v_writelane_b32 v243, s48, 41
	s_nop 1
	v_writelane_b32 v243, s49, 42
	v_writelane_b32 v243, s94, 43
	s_nop 1
	v_writelane_b32 v243, s95, 44
	v_writelane_b32 v243, s82, 45
	s_nop 1
	v_writelane_b32 v243, s83, 46
	v_writelane_b32 v243, s86, 47
	v_writelane_b32 v243, s80, 48
	v_writelane_b32 v243, s81, 49
	v_writelane_b32 v243, s87, 50
	v_writelane_b32 v243, s89, 51
	v_writelane_b32 v243, s95, 52
	s_branch .LBB0_414
